# attnB loop: LDS-DMA issue moved to mid-iteration gaps, softmax VALU kept out of the first two MFMA gaps after the barrier
# speedup vs baseline: 1.0149x; 1.0052x over previous
.Lb_loop:
	s_waitcnt lgkmcnt(0)
	v_mfma_f32_32x32x16_bf16 v[32:47], v[192:195], v[224:227], v[32:47]
	ds_read_b128 v[96:99], v146 offset:33280
	ds_read_b128 v[100:103], v147 offset:33280
	ds_read_b128 v[104:107], v148 offset:33280
	ds_read_b128 v[108:111], v149 offset:33280
	ds_read_b64_tr_b16 v[192:193], v179 offset:18688
	ds_read_b64_tr_b16 v[194:195], v179 offset:19200
	v_mfma_f32_32x32x16_bf16 v[48:63], v[196:199], v[224:227], v[48:63]
	ds_read_b64_tr_b16 v[196:197], v179 offset:22848
	ds_read_b64_tr_b16 v[198:199], v179 offset:23360
	v_mfma_f32_32x32x16_bf16 v[16:31], v[200:203], v[224:227], v[16:31]
	ds_read_b64_tr_b16 v[200:201], v179 offset:27008
	ds_read_b64_tr_b16 v[202:203], v179 offset:27520
	v_exp_f32_e32 v240, v80
	v_exp_f32_e32 v241, v81
	v_exp_f32_e32 v242, v82
	v_mfma_f32_32x32x16_bf16 v[0:15], v[204:207], v[224:227], v[0:15]
	ds_read_b64_tr_b16 v[204:205], v179 offset:31168
	ds_read_b64_tr_b16 v[206:207], v179 offset:31680
	v_exp_f32_e32 v243, v83
	v_exp_f32_e32 v244, v84
	v_exp_f32_e32 v245, v85
	s_waitcnt lgkmcnt(8)
	v_mfma_f32_32x32x16_bf16 v[112:127], v[96:99], v[128:131], v[64:79]
	ds_read_b128 v[96:99], v146 offset:37376
	v_add_f32_e32 v145, v240, v241
	v_cvt_pk_bf16_f32 v232, v240, v241
	v_exp_f32_e32 v246, v86
	v_exp_f32_e32 v247, v87
	v_mfma_f32_32x32x16_bf16 v[112:127], v[100:103], v[132:135], v[112:127]
	ds_read_b128 v[100:103], v147 offset:37376
	s_add_i32 s0, s50, 0xffff8000
	s_and_b32 s0, s0, 0x1f8000
	s_lshl_b32 s4, s0, 1
	s_add_i32 m0, s41, 0x18600
	s_nop 0
	buffer_load_dwordx4 v250, s[8:11], s4 offen lds
	s_add_i32 m0, s41, 0x1a600
	s_nop 0
	buffer_load_dwordx4 v250, s[8:11], s4 offen offset:128 lds
	v_add_f32_e32 v145, v145, v242
	v_add_f32_e32 v145, v145, v243
	v_cvt_pk_bf16_f32 v233, v242, v243
	v_exp_f32_e32 v240, v88
	v_mfma_f32_32x32x16_bf16 v[112:127], v[104:107], v[136:139], v[112:127]
	ds_read_b128 v[104:107], v148 offset:37376
	v_exp_f32_e32 v241, v89
	v_add_f32_e32 v145, v145, v244
	v_add_f32_e32 v145, v145, v245
	v_cvt_pk_bf16_f32 v234, v244, v245
	v_exp_f32_e32 v242, v90
	v_mfma_f32_32x32x16_bf16 v[112:127], v[108:111], v[140:143], v[112:127]
	ds_read_b128 v[108:111], v149 offset:37376
	s_add_i32 m0, s43, 0x18600
	s_nop 0
	buffer_load_dwordx4 v251, s[12:15], s4 offen lds
	s_add_i32 m0, s43, 0x1a600
	s_nop 0
	buffer_load_dwordx4 v251, s[12:15], s4 offen offset:128 lds
	v_exp_f32_e32 v243, v91
	v_add_f32_e32 v145, v145, v246
	v_add_f32_e32 v145, v145, v247
	v_cvt_pk_bf16_f32 v235, v246, v247
	v_mfma_f32_32x32x16_bf16 v[32:47], v[208:211], v[228:231], v[32:47]
	ds_read_b64_tr_b16 v[208:209], v179 offset:19712
	ds_read_b64_tr_b16 v[210:211], v179 offset:20224
	v_exp_f32_e32 v244, v92
	v_exp_f32_e32 v245, v93
	v_add_f32_e32 v145, v145, v240
	v_add_f32_e32 v145, v145, v241
	v_mfma_f32_32x32x16_bf16 v[48:63], v[212:215], v[228:231], v[48:63]
	ds_read_b64_tr_b16 v[212:213], v179 offset:23872
	ds_read_b64_tr_b16 v[214:215], v179 offset:24384
	v_cvt_pk_bf16_f32 v236, v240, v241
	v_exp_f32_e32 v246, v94
	v_exp_f32_e32 v247, v95
	v_mfma_f32_32x32x16_bf16 v[16:31], v[216:219], v[228:231], v[16:31]
	ds_read_b64_tr_b16 v[216:217], v179 offset:28032
	ds_read_b64_tr_b16 v[218:219], v179 offset:28544
	v_add_f32_e32 v145, v145, v242
	v_add_f32_e32 v145, v145, v243
	v_cvt_pk_bf16_f32 v237, v242, v243
	v_add_f32_e32 v145, v145, v244
	v_add_f32_e32 v145, v145, v245
	v_cvt_pk_bf16_f32 v238, v244, v245
	v_mfma_f32_32x32x16_bf16 v[0:15], v[220:223], v[228:231], v[0:15]
	ds_read_b64_tr_b16 v[220:221], v179 offset:32192
	ds_read_b64_tr_b16 v[222:223], v179 offset:32704
	v_add_f32_e32 v145, v145, v246
	v_add_f32_e32 v249, v145, v247
	v_cvt_pk_bf16_f32 v239, v246, v247
	v_add_f32_e32 v249, v248, v249
	v_cmp_lt_f32_e32 vcc, s3, v249
	v_add_f32_e32 v191, v191, v249
	s_waitcnt lgkmcnt(8)
	v_mfma_f32_32x32x16_bf16 v[80:95], v[96:99], v[128:131], v[64:79]
	v_exp_f32_e32 v240, v112
	v_exp_f32_e32 v241, v113
	v_mfma_f32_32x32x16_bf16 v[80:95], v[100:103], v[132:135], v[80:95]
	v_exp_f32_e32 v242, v114
	v_exp_f32_e32 v243, v115
	v_exp_f32_e32 v244, v116
	v_mfma_f32_32x32x16_bf16 v[80:95], v[104:107], v[136:139], v[80:95]
	v_exp_f32_e32 v245, v117
	v_add_f32_e32 v145, v240, v241
	v_cvt_pk_bf16_f32 v224, v240, v241
	v_mfma_f32_32x32x16_bf16 v[80:95], v[108:111], v[140:143], v[80:95]
	v_exp_f32_e32 v246, v118
	v_exp_f32_e32 v247, v119
	v_mfma_f32_32x32x16_bf16 v[32:47], v[192:195], v[232:235], v[32:47]
	ds_read_b64_tr_b16 v[192:193], v180 offset:0
	ds_read_b64_tr_b16 v[194:195], v180 offset:512
	v_add_f32_e32 v145, v145, v242
	v_add_f32_e32 v145, v145, v243
	v_cvt_pk_bf16_f32 v225, v242, v243
	v_exp_f32_e32 v240, v120
	v_mfma_f32_32x32x16_bf16 v[48:63], v[196:199], v[232:235], v[48:63]
	ds_read_b64_tr_b16 v[196:197], v180 offset:4160
	ds_read_b64_tr_b16 v[198:199], v180 offset:4672
	v_exp_f32_e32 v241, v121
	v_add_f32_e32 v145, v145, v244
	v_add_f32_e32 v145, v145, v245
	v_cvt_pk_bf16_f32 v226, v244, v245
	v_mfma_f32_32x32x16_bf16 v[16:31], v[200:203], v[232:235], v[16:31]
	ds_read_b64_tr_b16 v[200:201], v180 offset:8320
	ds_read_b64_tr_b16 v[202:203], v180 offset:8832
	v_exp_f32_e32 v242, v122
	v_exp_f32_e32 v243, v123
	v_mfma_f32_32x32x16_bf16 v[0:15], v[204:207], v[232:235], v[0:15]
	ds_read_b64_tr_b16 v[204:205], v180 offset:12480
	ds_read_b64_tr_b16 v[206:207], v180 offset:12992
	v_add_f32_e32 v145, v145, v246
	v_add_f32_e32 v145, v145, v247
	v_cvt_pk_bf16_f32 v227, v246, v247
	v_exp_f32_e32 v244, v124
	s_waitcnt lgkmcnt(8)
	v_mfma_f32_32x32x16_bf16 v[32:47], v[208:211], v[236:239], v[32:47]
	ds_read_b64_tr_b16 v[208:209], v180 offset:1024
	ds_read_b64_tr_b16 v[210:211], v180 offset:1536
	v_exp_f32_e32 v245, v125
	v_add_f32_e32 v145, v145, v240
	v_add_f32_e32 v145, v145, v241
	v_mfma_f32_32x32x16_bf16 v[48:63], v[212:215], v[236:239], v[48:63]
	ds_read_b64_tr_b16 v[212:213], v180 offset:5184
	ds_read_b64_tr_b16 v[214:215], v180 offset:5696
	v_cvt_pk_bf16_f32 v228, v240, v241
	v_exp_f32_e32 v246, v126
	v_exp_f32_e32 v247, v127
	v_mfma_f32_32x32x16_bf16 v[16:31], v[216:219], v[236:239], v[16:31]
	ds_read_b64_tr_b16 v[216:217], v180 offset:9344
	ds_read_b64_tr_b16 v[218:219], v180 offset:9856
	v_add_f32_e32 v145, v145, v242
	v_add_f32_e32 v145, v145, v243
	v_cvt_pk_bf16_f32 v229, v242, v243
	v_add_f32_e32 v145, v145, v244
	v_mfma_f32_32x32x16_bf16 v[0:15], v[220:223], v[236:239], v[0:15]
	ds_read_b64_tr_b16 v[220:221], v180 offset:13504
	ds_read_b64_tr_b16 v[222:223], v180 offset:14016
	v_add_f32_e32 v145, v145, v245
	v_cvt_pk_bf16_f32 v230, v244, v245
	v_add_f32_e32 v145, v145, v246
	v_add_f32_e32 v248, v145, v247
	v_cvt_pk_bf16_f32 v231, v246, v247
	s_cbranch_vccz .Lb_cont0
	s_branch .Lb_rare0
.Lb_cont0:
	s_waitcnt vmcnt(4)
	s_barrier
	s_waitcnt lgkmcnt(0)
	v_mfma_f32_32x32x16_bf16 v[32:47], v[192:195], v[224:227], v[32:47]
	ds_read_b128 v[96:99], v150 offset:0
	ds_read_b128 v[100:103], v151 offset:0
	ds_read_b128 v[104:107], v152 offset:0
	ds_read_b128 v[108:111], v153 offset:0
	ds_read_b64_tr_b16 v[192:193], v180 offset:2048
	ds_read_b64_tr_b16 v[194:195], v180 offset:2560
	v_mfma_f32_32x32x16_bf16 v[48:63], v[196:199], v[224:227], v[48:63]
	ds_read_b64_tr_b16 v[196:197], v180 offset:6208
	ds_read_b64_tr_b16 v[198:199], v180 offset:6720
	v_mfma_f32_32x32x16_bf16 v[16:31], v[200:203], v[224:227], v[16:31]
	ds_read_b64_tr_b16 v[200:201], v180 offset:10368
	ds_read_b64_tr_b16 v[202:203], v180 offset:10880
	v_exp_f32_e32 v240, v80
	v_exp_f32_e32 v241, v81
	v_exp_f32_e32 v242, v82
	v_mfma_f32_32x32x16_bf16 v[0:15], v[204:207], v[224:227], v[0:15]
	ds_read_b64_tr_b16 v[204:205], v180 offset:14528
	ds_read_b64_tr_b16 v[206:207], v180 offset:15040
	v_exp_f32_e32 v243, v83
	v_exp_f32_e32 v244, v84
	v_exp_f32_e32 v245, v85
	s_waitcnt lgkmcnt(8)
	v_mfma_f32_32x32x16_bf16 v[112:127], v[96:99], v[128:131], v[64:79]
	ds_read_b128 v[96:99], v150 offset:4096
	v_add_f32_e32 v145, v240, v241
	v_cvt_pk_bf16_f32 v232, v240, v241
	v_exp_f32_e32 v246, v86
	v_exp_f32_e32 v247, v87
	v_mfma_f32_32x32x16_bf16 v[112:127], v[100:103], v[132:135], v[112:127]
	ds_read_b128 v[100:103], v151 offset:4096
	s_cmp_gt_u32 s6, 59
	s_cbranch_scc1 .Lb_nodma_k1
	s_and_b32 s0, s50, 0x1f8000
	s_lshl_b32 s4, s0, 1
	s_add_i32 m0, s41, 0x0
	s_nop 0
	buffer_load_dwordx4 v250, s[8:11], s4 offen lds
	s_add_i32 m0, s41, 0x2000
	s_nop 0
	buffer_load_dwordx4 v250, s[8:11], s4 offen offset:128 lds
	s_branch .Lb_dmaok_k1

.Lb_dmaok_k1:
	v_add_f32_e32 v145, v145, v242
	v_add_f32_e32 v145, v145, v243
	v_cvt_pk_bf16_f32 v233, v242, v243
	v_exp_f32_e32 v240, v88
	v_mfma_f32_32x32x16_bf16 v[112:127], v[104:107], v[136:139], v[112:127]
	ds_read_b128 v[104:107], v152 offset:4096
	v_exp_f32_e32 v241, v89
	v_add_f32_e32 v145, v145, v244
	v_add_f32_e32 v145, v145, v245
	v_cvt_pk_bf16_f32 v234, v244, v245
	v_exp_f32_e32 v242, v90
	v_mfma_f32_32x32x16_bf16 v[112:127], v[108:111], v[140:143], v[112:127]
	ds_read_b128 v[108:111], v153 offset:4096
	s_cmp_gt_u32 s6, 59
	s_cbranch_scc1 .Lb_nodma_v1
	s_add_i32 m0, s43, 0x0
	s_nop 0
	buffer_load_dwordx4 v251, s[12:15], s4 offen lds
	s_add_i32 m0, s43, 0x2000
	s_nop 0
	buffer_load_dwordx4 v251, s[12:15], s4 offen offset:128 lds
.Lb_nodma_v1:
	v_exp_f32_e32 v243, v91
	v_add_f32_e32 v145, v145, v246
	v_add_f32_e32 v145, v145, v247
	v_cvt_pk_bf16_f32 v235, v246, v247
	v_mfma_f32_32x32x16_bf16 v[32:47], v[208:211], v[228:231], v[32:47]
	ds_read_b64_tr_b16 v[208:209], v180 offset:3072
	ds_read_b64_tr_b16 v[210:211], v180 offset:3584
	v_exp_f32_e32 v244, v92
	v_exp_f32_e32 v245, v93
	v_add_f32_e32 v145, v145, v240
	v_add_f32_e32 v145, v145, v241
	v_mfma_f32_32x32x16_bf16 v[48:63], v[212:215], v[228:231], v[48:63]
	ds_read_b64_tr_b16 v[212:213], v180 offset:7232
	ds_read_b64_tr_b16 v[214:215], v180 offset:7744
	v_cvt_pk_bf16_f32 v236, v240, v241
	v_exp_f32_e32 v246, v94
	v_exp_f32_e32 v247, v95
	v_mfma_f32_32x32x16_bf16 v[16:31], v[216:219], v[228:231], v[16:31]
	ds_read_b64_tr_b16 v[216:217], v180 offset:11392
	ds_read_b64_tr_b16 v[218:219], v180 offset:11904
	v_add_f32_e32 v145, v145, v242
	v_add_f32_e32 v145, v145, v243
	v_cvt_pk_bf16_f32 v237, v242, v243
	v_add_f32_e32 v145, v145, v244
	v_add_f32_e32 v145, v145, v245
	v_cvt_pk_bf16_f32 v238, v244, v245
	v_mfma_f32_32x32x16_bf16 v[0:15], v[220:223], v[228:231], v[0:15]
	ds_read_b64_tr_b16 v[220:221], v180 offset:15552
	ds_read_b64_tr_b16 v[222:223], v180 offset:16064
	v_add_f32_e32 v145, v145, v246
	v_add_f32_e32 v249, v145, v247
	v_cvt_pk_bf16_f32 v239, v246, v247
	v_add_f32_e32 v249, v248, v249
	v_cmp_lt_f32_e32 vcc, s3, v249
	v_add_f32_e32 v191, v191, v249
	s_waitcnt lgkmcnt(8)
	v_mfma_f32_32x32x16_bf16 v[80:95], v[96:99], v[128:131], v[64:79]
	v_exp_f32_e32 v240, v112
	v_exp_f32_e32 v241, v113
	v_mfma_f32_32x32x16_bf16 v[80:95], v[100:103], v[132:135], v[80:95]
	v_exp_f32_e32 v242, v114
	v_exp_f32_e32 v243, v115
	v_exp_f32_e32 v244, v116
	v_mfma_f32_32x32x16_bf16 v[80:95], v[104:107], v[136:139], v[80:95]
	v_exp_f32_e32 v245, v117
	v_add_f32_e32 v145, v240, v241
	v_cvt_pk_bf16_f32 v224, v240, v241
	v_mfma_f32_32x32x16_bf16 v[80:95], v[108:111], v[140:143], v[80:95]
	v_exp_f32_e32 v246, v118
	v_exp_f32_e32 v247, v119
	v_mfma_f32_32x32x16_bf16 v[32:47], v[192:195], v[232:235], v[32:47]
	ds_read_b64_tr_b16 v[192:193], v182 offset:0
	ds_read_b64_tr_b16 v[194:195], v182 offset:512
	v_add_f32_e32 v145, v145, v242
	v_add_f32_e32 v145, v145, v243
	v_cvt_pk_bf16_f32 v225, v242, v243
	v_exp_f32_e32 v240, v120
	v_mfma_f32_32x32x16_bf16 v[48:63], v[196:199], v[232:235], v[48:63]
	ds_read_b64_tr_b16 v[196:197], v182 offset:4160
	ds_read_b64_tr_b16 v[198:199], v182 offset:4672
	v_exp_f32_e32 v241, v121
	v_add_f32_e32 v145, v145, v244
	v_add_f32_e32 v145, v145, v245
	v_cvt_pk_bf16_f32 v226, v244, v245
	v_mfma_f32_32x32x16_bf16 v[16:31], v[200:203], v[232:235], v[16:31]
	ds_read_b64_tr_b16 v[200:201], v182 offset:8320
	ds_read_b64_tr_b16 v[202:203], v182 offset:8832
	v_exp_f32_e32 v242, v122
	v_exp_f32_e32 v243, v123
	v_mfma_f32_32x32x16_bf16 v[0:15], v[204:207], v[232:235], v[0:15]
	ds_read_b64_tr_b16 v[204:205], v182 offset:12480
	ds_read_b64_tr_b16 v[206:207], v182 offset:12992
	v_add_f32_e32 v145, v145, v246
	v_add_f32_e32 v145, v145, v247
	v_cvt_pk_bf16_f32 v227, v246, v247
	v_exp_f32_e32 v244, v124
	s_waitcnt lgkmcnt(8)
	v_mfma_f32_32x32x16_bf16 v[32:47], v[208:211], v[236:239], v[32:47]
	ds_read_b64_tr_b16 v[208:209], v182 offset:1024
	ds_read_b64_tr_b16 v[210:211], v182 offset:1536
	v_exp_f32_e32 v245, v125
	v_add_f32_e32 v145, v145, v240
	v_add_f32_e32 v145, v145, v241
	v_mfma_f32_32x32x16_bf16 v[48:63], v[212:215], v[236:239], v[48:63]
	ds_read_b64_tr_b16 v[212:213], v182 offset:5184
	ds_read_b64_tr_b16 v[214:215], v182 offset:5696
	v_cvt_pk_bf16_f32 v228, v240, v241
	v_exp_f32_e32 v246, v126
	v_exp_f32_e32 v247, v127
	v_mfma_f32_32x32x16_bf16 v[16:31], v[216:219], v[236:239], v[16:31]
	ds_read_b64_tr_b16 v[216:217], v182 offset:9344
	ds_read_b64_tr_b16 v[218:219], v182 offset:9856
	v_add_f32_e32 v145, v145, v242
	v_add_f32_e32 v145, v145, v243
	v_cvt_pk_bf16_f32 v229, v242, v243
	v_add_f32_e32 v145, v145, v244
	v_mfma_f32_32x32x16_bf16 v[0:15], v[220:223], v[236:239], v[0:15]
	ds_read_b64_tr_b16 v[220:221], v182 offset:13504
	ds_read_b64_tr_b16 v[222:223], v182 offset:14016
	v_add_f32_e32 v145, v145, v245
	v_cvt_pk_bf16_f32 v230, v244, v245
	v_add_f32_e32 v145, v145, v246
	v_add_f32_e32 v248, v145, v247
	v_cvt_pk_bf16_f32 v231, v246, v247
	s_cbranch_vccz .Lb_cont1
	s_branch .Lb_rare1
.Lb_cont1:
	s_waitcnt vmcnt(4)
	s_barrier
	s_waitcnt lgkmcnt(0)
	v_mfma_f32_32x32x16_bf16 v[32:47], v[192:195], v[224:227], v[32:47]
	ds_read_b128 v[96:99], v150 offset:33280
	ds_read_b128 v[100:103], v151 offset:33280
	ds_read_b128 v[104:107], v152 offset:33280
	ds_read_b128 v[108:111], v153 offset:33280
	ds_read_b64_tr_b16 v[192:193], v182 offset:2048
	ds_read_b64_tr_b16 v[194:195], v182 offset:2560
	v_mfma_f32_32x32x16_bf16 v[48:63], v[196:199], v[224:227], v[48:63]
	ds_read_b64_tr_b16 v[196:197], v182 offset:6208
	ds_read_b64_tr_b16 v[198:199], v182 offset:6720
	v_mfma_f32_32x32x16_bf16 v[16:31], v[200:203], v[224:227], v[16:31]
	ds_read_b64_tr_b16 v[200:201], v182 offset:10368
	ds_read_b64_tr_b16 v[202:203], v182 offset:10880
	v_exp_f32_e32 v240, v80
	v_exp_f32_e32 v241, v81
	v_exp_f32_e32 v242, v82
	v_mfma_f32_32x32x16_bf16 v[0:15], v[204:207], v[224:227], v[0:15]
	ds_read_b64_tr_b16 v[204:205], v182 offset:14528
	ds_read_b64_tr_b16 v[206:207], v182 offset:15040
	v_exp_f32_e32 v243, v83
	v_exp_f32_e32 v244, v84
	v_exp_f32_e32 v245, v85
	s_waitcnt lgkmcnt(8)
	v_mfma_f32_32x32x16_bf16 v[112:127], v[96:99], v[128:131], v[64:79]
	ds_read_b128 v[96:99], v150 offset:37376
	v_add_f32_e32 v145, v240, v241
	v_cvt_pk_bf16_f32 v232, v240, v241
	v_exp_f32_e32 v246, v86
	v_exp_f32_e32 v247, v87
	v_mfma_f32_32x32x16_bf16 v[112:127], v[100:103], v[132:135], v[112:127]
	ds_read_b128 v[100:103], v151 offset:37376
	s_cmp_gt_u32 s6, 59
	s_cbranch_scc1 .Lb_nodma_k2
	s_add_i32 s0, s50, 0x8000
	s_and_b32 s0, s0, 0x1f8000
	s_lshl_b32 s4, s0, 1
	s_add_i32 m0, s41, 0x8200
	s_nop 0
	buffer_load_dwordx4 v250, s[8:11], s4 offen lds
	s_add_i32 m0, s41, 0xa200
	s_nop 0
	buffer_load_dwordx4 v250, s[8:11], s4 offen offset:128 lds
	s_branch .Lb_dmaok_k2

.Lb_dmaok_k2:
	v_add_f32_e32 v145, v145, v242
	v_add_f32_e32 v145, v145, v243
	v_cvt_pk_bf16_f32 v233, v242, v243
	v_exp_f32_e32 v240, v88
	v_mfma_f32_32x32x16_bf16 v[112:127], v[104:107], v[136:139], v[112:127]
	ds_read_b128 v[104:107], v152 offset:37376
	v_exp_f32_e32 v241, v89
	v_add_f32_e32 v145, v145, v244
	v_add_f32_e32 v145, v145, v245
	v_cvt_pk_bf16_f32 v234, v244, v245
	v_exp_f32_e32 v242, v90
	v_mfma_f32_32x32x16_bf16 v[112:127], v[108:111], v[140:143], v[112:127]
	ds_read_b128 v[108:111], v153 offset:37376
	s_cmp_gt_u32 s6, 59
	s_cbranch_scc1 .Lb_nodma_v2
	s_add_i32 m0, s43, 0x8200
	s_nop 0
	buffer_load_dwordx4 v251, s[12:15], s4 offen lds
	s_add_i32 m0, s43, 0xa200
	s_nop 0
	buffer_load_dwordx4 v251, s[12:15], s4 offen offset:128 lds
.Lb_nodma_v2:
	v_exp_f32_e32 v243, v91
	v_add_f32_e32 v145, v145, v246
	v_add_f32_e32 v145, v145, v247
	v_cvt_pk_bf16_f32 v235, v246, v247
	v_mfma_f32_32x32x16_bf16 v[32:47], v[208:211], v[228:231], v[32:47]
	ds_read_b64_tr_b16 v[208:209], v182 offset:3072
	ds_read_b64_tr_b16 v[210:211], v182 offset:3584
	v_exp_f32_e32 v244, v92
	v_exp_f32_e32 v245, v93
	v_add_f32_e32 v145, v145, v240
	v_add_f32_e32 v145, v145, v241
	v_mfma_f32_32x32x16_bf16 v[48:63], v[212:215], v[228:231], v[48:63]
	ds_read_b64_tr_b16 v[212:213], v182 offset:7232
	ds_read_b64_tr_b16 v[214:215], v182 offset:7744
	v_cvt_pk_bf16_f32 v236, v240, v241
	v_exp_f32_e32 v246, v94
	v_exp_f32_e32 v247, v95
	v_mfma_f32_32x32x16_bf16 v[16:31], v[216:219], v[228:231], v[16:31]
	ds_read_b64_tr_b16 v[216:217], v182 offset:11392
	ds_read_b64_tr_b16 v[218:219], v182 offset:11904
	v_add_f32_e32 v145, v145, v242
	v_add_f32_e32 v145, v145, v243
	v_cvt_pk_bf16_f32 v237, v242, v243
	v_add_f32_e32 v145, v145, v244
	v_add_f32_e32 v145, v145, v245
	v_cvt_pk_bf16_f32 v238, v244, v245
	v_mfma_f32_32x32x16_bf16 v[0:15], v[220:223], v[228:231], v[0:15]
	ds_read_b64_tr_b16 v[220:221], v182 offset:15552
	ds_read_b64_tr_b16 v[222:223], v182 offset:16064
	v_add_f32_e32 v145, v145, v246
	v_add_f32_e32 v249, v145, v247
	v_cvt_pk_bf16_f32 v239, v246, v247
	v_add_f32_e32 v249, v248, v249
	v_cmp_lt_f32_e32 vcc, s3, v249
	v_add_f32_e32 v191, v191, v249
	s_waitcnt lgkmcnt(8)
	v_mfma_f32_32x32x16_bf16 v[80:95], v[96:99], v[128:131], v[64:79]
	v_exp_f32_e32 v240, v112
	v_exp_f32_e32 v241, v113
	v_mfma_f32_32x32x16_bf16 v[80:95], v[100:103], v[132:135], v[80:95]
	v_exp_f32_e32 v242, v114
	v_exp_f32_e32 v243, v115
	v_exp_f32_e32 v244, v116
	v_mfma_f32_32x32x16_bf16 v[80:95], v[104:107], v[136:139], v[80:95]
	v_exp_f32_e32 v245, v117
	v_add_f32_e32 v145, v240, v241
	v_cvt_pk_bf16_f32 v224, v240, v241
	v_mfma_f32_32x32x16_bf16 v[80:95], v[108:111], v[140:143], v[80:95]
	v_exp_f32_e32 v246, v118
	v_exp_f32_e32 v247, v119
	v_mfma_f32_32x32x16_bf16 v[32:47], v[192:195], v[232:235], v[32:47]
	ds_read_b64_tr_b16 v[192:193], v182 offset:33280
	ds_read_b64_tr_b16 v[194:195], v182 offset:33792
	v_add_f32_e32 v145, v145, v242
	v_add_f32_e32 v145, v145, v243
	v_cvt_pk_bf16_f32 v225, v242, v243
	v_exp_f32_e32 v240, v120
	v_mfma_f32_32x32x16_bf16 v[48:63], v[196:199], v[232:235], v[48:63]
	ds_read_b64_tr_b16 v[196:197], v182 offset:37440
	ds_read_b64_tr_b16 v[198:199], v182 offset:37952
	v_exp_f32_e32 v241, v121
	v_add_f32_e32 v145, v145, v244
	v_add_f32_e32 v145, v145, v245
	v_cvt_pk_bf16_f32 v226, v244, v245
	v_mfma_f32_32x32x16_bf16 v[16:31], v[200:203], v[232:235], v[16:31]
	ds_read_b64_tr_b16 v[200:201], v182 offset:41600
	ds_read_b64_tr_b16 v[202:203], v182 offset:42112
	v_exp_f32_e32 v242, v122
	v_exp_f32_e32 v243, v123
	v_mfma_f32_32x32x16_bf16 v[0:15], v[204:207], v[232:235], v[0:15]
	ds_read_b64_tr_b16 v[204:205], v182 offset:45760
	ds_read_b64_tr_b16 v[206:207], v182 offset:46272
	v_add_f32_e32 v145, v145, v246
	v_add_f32_e32 v145, v145, v247
	v_cvt_pk_bf16_f32 v227, v246, v247
	v_exp_f32_e32 v244, v124
	s_waitcnt lgkmcnt(8)
	v_mfma_f32_32x32x16_bf16 v[32:47], v[208:211], v[236:239], v[32:47]
	ds_read_b64_tr_b16 v[208:209], v182 offset:34304
	ds_read_b64_tr_b16 v[210:211], v182 offset:34816
	v_exp_f32_e32 v245, v125
	v_add_f32_e32 v145, v145, v240
	v_add_f32_e32 v145, v145, v241
	v_mfma_f32_32x32x16_bf16 v[48:63], v[212:215], v[236:239], v[48:63]
	ds_read_b64_tr_b16 v[212:213], v182 offset:38464
	ds_read_b64_tr_b16 v[214:215], v182 offset:38976
	v_cvt_pk_bf16_f32 v228, v240, v241
	v_exp_f32_e32 v246, v126
	v_exp_f32_e32 v247, v127
	v_mfma_f32_32x32x16_bf16 v[16:31], v[216:219], v[236:239], v[16:31]
	ds_read_b64_tr_b16 v[216:217], v182 offset:42624
	ds_read_b64_tr_b16 v[218:219], v182 offset:43136
	v_add_f32_e32 v145, v145, v242
	v_add_f32_e32 v145, v145, v243
	v_cvt_pk_bf16_f32 v229, v242, v243
	v_add_f32_e32 v145, v145, v244
	v_mfma_f32_32x32x16_bf16 v[0:15], v[220:223], v[236:239], v[0:15]
	ds_read_b64_tr_b16 v[220:221], v182 offset:46784
	ds_read_b64_tr_b16 v[222:223], v182 offset:47296
	v_add_f32_e32 v145, v145, v245
	v_cvt_pk_bf16_f32 v230, v244, v245
	v_add_f32_e32 v145, v145, v246
	v_add_f32_e32 v248, v145, v247
	v_cvt_pk_bf16_f32 v231, v246, v247
	s_cbranch_vccz .Lb_cont2
	s_branch .Lb_rare2
.Lb_cont2:
	s_waitcnt vmcnt(4)
	s_barrier
	s_cmp_gt_u32 s6, 59
	s_cbranch_scc1 .Lb_final
	s_waitcnt lgkmcnt(0)
	v_mfma_f32_32x32x16_bf16 v[32:47], v[192:195], v[224:227], v[32:47]
	ds_read_b128 v[96:99], v146 offset:0
	ds_read_b128 v[100:103], v147 offset:0
	ds_read_b128 v[104:107], v148 offset:0
	ds_read_b128 v[108:111], v149 offset:0
	ds_read_b64_tr_b16 v[192:193], v182 offset:35328
	ds_read_b64_tr_b16 v[194:195], v182 offset:35840
	v_mfma_f32_32x32x16_bf16 v[48:63], v[196:199], v[224:227], v[48:63]
	ds_read_b64_tr_b16 v[196:197], v182 offset:39488
	ds_read_b64_tr_b16 v[198:199], v182 offset:40000
	v_mfma_f32_32x32x16_bf16 v[16:31], v[200:203], v[224:227], v[16:31]
	ds_read_b64_tr_b16 v[200:201], v182 offset:43648
	ds_read_b64_tr_b16 v[202:203], v182 offset:44160
	v_exp_f32_e32 v240, v80
	v_exp_f32_e32 v241, v81
	v_exp_f32_e32 v242, v82
	v_mfma_f32_32x32x16_bf16 v[0:15], v[204:207], v[224:227], v[0:15]
	ds_read_b64_tr_b16 v[204:205], v182 offset:47808
	ds_read_b64_tr_b16 v[206:207], v182 offset:48320
	v_exp_f32_e32 v243, v83
	v_exp_f32_e32 v244, v84
	v_exp_f32_e32 v245, v85
	s_waitcnt lgkmcnt(8)
	v_mfma_f32_32x32x16_bf16 v[112:127], v[96:99], v[128:131], v[64:79]
	ds_read_b128 v[96:99], v146 offset:4096
	v_add_f32_e32 v145, v240, v241
	v_cvt_pk_bf16_f32 v232, v240, v241
	v_exp_f32_e32 v246, v86
	v_exp_f32_e32 v247, v87
	v_mfma_f32_32x32x16_bf16 v[112:127], v[100:103], v[132:135], v[112:127]
	ds_read_b128 v[100:103], v147 offset:4096
	s_add_i32 s0, s50, 0x10000
	s_and_b32 s0, s0, 0x1f8000
	s_lshl_b32 s4, s0, 1
	s_add_i32 m0, s41, 0x10400
	s_nop 0
	buffer_load_dwordx4 v250, s[8:11], s4 offen lds
	s_add_i32 m0, s41, 0x12400
	s_nop 0
	buffer_load_dwordx4 v250, s[8:11], s4 offen offset:128 lds
	v_add_f32_e32 v145, v145, v242
	v_add_f32_e32 v145, v145, v243
	v_cvt_pk_bf16_f32 v233, v242, v243
	v_exp_f32_e32 v240, v88
	v_mfma_f32_32x32x16_bf16 v[112:127], v[104:107], v[136:139], v[112:127]
	ds_read_b128 v[104:107], v148 offset:4096
	v_exp_f32_e32 v241, v89
	v_add_f32_e32 v145, v145, v244
	v_add_f32_e32 v145, v145, v245
	v_cvt_pk_bf16_f32 v234, v244, v245
	v_exp_f32_e32 v242, v90
	v_mfma_f32_32x32x16_bf16 v[112:127], v[108:111], v[140:143], v[112:127]
	ds_read_b128 v[108:111], v149 offset:4096
	s_add_i32 m0, s43, 0x10400
	s_nop 0
	buffer_load_dwordx4 v251, s[12:15], s4 offen lds
	s_add_i32 m0, s43, 0x12400
	s_nop 0
	buffer_load_dwordx4 v251, s[12:15], s4 offen offset:128 lds
	v_exp_f32_e32 v243, v91
	v_add_f32_e32 v145, v145, v246
	v_add_f32_e32 v145, v145, v247
	v_cvt_pk_bf16_f32 v235, v246, v247
	v_mfma_f32_32x32x16_bf16 v[32:47], v[208:211], v[228:231], v[32:47]
	ds_read_b64_tr_b16 v[208:209], v182 offset:36352
	ds_read_b64_tr_b16 v[210:211], v182 offset:36864
	v_exp_f32_e32 v244, v92
	v_exp_f32_e32 v245, v93
	v_add_f32_e32 v145, v145, v240
	v_add_f32_e32 v145, v145, v241
	v_mfma_f32_32x32x16_bf16 v[48:63], v[212:215], v[228:231], v[48:63]
	ds_read_b64_tr_b16 v[212:213], v182 offset:40512
	ds_read_b64_tr_b16 v[214:215], v182 offset:41024
	v_cvt_pk_bf16_f32 v236, v240, v241
	v_exp_f32_e32 v246, v94
	v_exp_f32_e32 v247, v95
	v_mfma_f32_32x32x16_bf16 v[16:31], v[216:219], v[228:231], v[16:31]
	ds_read_b64_tr_b16 v[216:217], v182 offset:44672
	ds_read_b64_tr_b16 v[218:219], v182 offset:45184
	v_add_f32_e32 v145, v145, v242
	v_add_f32_e32 v145, v145, v243
	v_cvt_pk_bf16_f32 v237, v242, v243
	v_add_f32_e32 v145, v145, v244
	v_add_f32_e32 v145, v145, v245
	v_cvt_pk_bf16_f32 v238, v244, v245
	v_mfma_f32_32x32x16_bf16 v[0:15], v[220:223], v[228:231], v[0:15]
	ds_read_b64_tr_b16 v[220:221], v182 offset:48832
	ds_read_b64_tr_b16 v[222:223], v182 offset:49344
	v_add_f32_e32 v145, v145, v246
	v_add_f32_e32 v249, v145, v247
	v_cvt_pk_bf16_f32 v239, v246, v247
	v_add_f32_e32 v249, v248, v249
	v_cmp_lt_f32_e32 vcc, s3, v249
	v_add_f32_e32 v191, v191, v249
	s_waitcnt lgkmcnt(8)
	v_mfma_f32_32x32x16_bf16 v[80:95], v[96:99], v[128:131], v[64:79]
	v_exp_f32_e32 v240, v112
	v_exp_f32_e32 v241, v113
	v_mfma_f32_32x32x16_bf16 v[80:95], v[100:103], v[132:135], v[80:95]
	v_exp_f32_e32 v242, v114
	v_exp_f32_e32 v243, v115
	v_exp_f32_e32 v244, v116
	v_mfma_f32_32x32x16_bf16 v[80:95], v[104:107], v[136:139], v[80:95]
	v_exp_f32_e32 v245, v117
	v_add_f32_e32 v145, v240, v241
	v_cvt_pk_bf16_f32 v224, v240, v241
	v_mfma_f32_32x32x16_bf16 v[80:95], v[108:111], v[140:143], v[80:95]
	v_exp_f32_e32 v246, v118
	v_exp_f32_e32 v247, v119
	v_mfma_f32_32x32x16_bf16 v[32:47], v[192:195], v[232:235], v[32:47]
	ds_read_b64_tr_b16 v[192:193], v179 offset:16640
	ds_read_b64_tr_b16 v[194:195], v179 offset:17152
	v_add_f32_e32 v145, v145, v242
	v_add_f32_e32 v145, v145, v243
	v_cvt_pk_bf16_f32 v225, v242, v243
	v_exp_f32_e32 v240, v120
	v_mfma_f32_32x32x16_bf16 v[48:63], v[196:199], v[232:235], v[48:63]
	ds_read_b64_tr_b16 v[196:197], v179 offset:20800
	ds_read_b64_tr_b16 v[198:199], v179 offset:21312
	v_exp_f32_e32 v241, v121
	v_add_f32_e32 v145, v145, v244
	v_add_f32_e32 v145, v145, v245
	v_cvt_pk_bf16_f32 v226, v244, v245
	v_mfma_f32_32x32x16_bf16 v[16:31], v[200:203], v[232:235], v[16:31]
	ds_read_b64_tr_b16 v[200:201], v179 offset:24960
	ds_read_b64_tr_b16 v[202:203], v179 offset:25472
	v_exp_f32_e32 v242, v122
	v_exp_f32_e32 v243, v123
	v_mfma_f32_32x32x16_bf16 v[0:15], v[204:207], v[232:235], v[0:15]
	ds_read_b64_tr_b16 v[204:205], v179 offset:29120
	ds_read_b64_tr_b16 v[206:207], v179 offset:29632
	v_add_f32_e32 v145, v145, v246
	v_add_f32_e32 v145, v145, v247
	v_cvt_pk_bf16_f32 v227, v246, v247
	v_exp_f32_e32 v244, v124
	s_waitcnt lgkmcnt(8)
	v_mfma_f32_32x32x16_bf16 v[32:47], v[208:211], v[236:239], v[32:47]
	ds_read_b64_tr_b16 v[208:209], v179 offset:17664
	ds_read_b64_tr_b16 v[210:211], v179 offset:18176
	v_exp_f32_e32 v245, v125
	v_add_f32_e32 v145, v145, v240
	v_add_f32_e32 v145, v145, v241
	v_mfma_f32_32x32x16_bf16 v[48:63], v[212:215], v[236:239], v[48:63]
	ds_read_b64_tr_b16 v[212:213], v179 offset:21824
	ds_read_b64_tr_b16 v[214:215], v179 offset:22336
	v_cvt_pk_bf16_f32 v228, v240, v241
	v_exp_f32_e32 v246, v126
	v_exp_f32_e32 v247, v127
	v_mfma_f32_32x32x16_bf16 v[16:31], v[216:219], v[236:239], v[16:31]
	ds_read_b64_tr_b16 v[216:217], v179 offset:25984
	ds_read_b64_tr_b16 v[218:219], v179 offset:26496
	v_add_f32_e32 v145, v145, v242
	v_add_f32_e32 v145, v145, v243
	v_cvt_pk_bf16_f32 v229, v242, v243
	v_add_f32_e32 v145, v145, v244
	v_mfma_f32_32x32x16_bf16 v[0:15], v[220:223], v[236:239], v[0:15]
	ds_read_b64_tr_b16 v[220:221], v179 offset:30144
	ds_read_b64_tr_b16 v[222:223], v179 offset:30656
	v_add_f32_e32 v145, v145, v245
	v_cvt_pk_bf16_f32 v230, v244, v245
	v_add_f32_e32 v145, v145, v246
	v_add_f32_e32 v248, v145, v247
	v_cvt_pk_bf16_f32 v231, v246, v247
	s_cbranch_vccz .Lb_cont3
	s_branch .Lb_rare3
